# XCD-local seams: arrival through a per-XCD line of 32 words in that L2 (plain store of the seam generation, lanes 0-31 poll) instead of a device-scope atomic counter
# speedup vs baseline: 1.0090x; 1.0090x over previous
.Llb_loc_s1:
	v_cmp_gt_u32_e32 vcc, 32, v0
	s_and_saveexec_b64 s[2:3], vcc
	s_cbranch_execz .Llb_done_s1
	v_readlane_b32 s4, v254, 14
	v_readlane_b32 s10, v254, 12
	v_readlane_b32 s11, v254, 13
	s_lshl_b32 s4, s4, 7
	s_add_u32 s4, s10, s4
	s_addc_u32 s5, s11, 0
	s_lshr_b32 s98, s24, 3
	s_lshl_b32 s98, s98, 2
	s_add_i32 s98, s98, 0x4000
	v_mov_b32_e32 v3, s98
	v_mov_b32_e32 v4, 1
	global_store_dword v3, v4, s[4:5]
	v_lshlrev_b32_e32 v3, 2, v0
	v_add_u32_e32 v3, 0x4000, v3
	s_mov_b32 s99, 0
.Llb_spin_s1:
	global_load_dword v2, v3, s[4:5] sc1
	s_waitcnt vmcnt(0)
	v_cmp_gt_u32_e32 vcc, 1, v2
	s_cbranch_vccz .Llb_acq_s1
	s_sleep 1
	s_add_i32 s99, s99, 1
	s_cmp_lt_u32 s99, 0x40000
	s_cbranch_scc1 .Llb_spin_s1

.Llb_loc_s2:
	v_cmp_gt_u32_e32 vcc, 32, v0
	s_and_saveexec_b64 s[0:1], vcc
	s_cbranch_execz .Llb_done_s2
	v_readlane_b32 s4, v254, 14
	v_readlane_b32 s10, v254, 12
	v_readlane_b32 s11, v254, 13
	s_lshl_b32 s4, s4, 7
	s_add_u32 s4, s10, s4
	s_addc_u32 s5, s11, 0
	s_lshr_b32 s98, s24, 3
	s_lshl_b32 s98, s98, 2
	s_add_i32 s98, s98, 0x4000
	v_mov_b32_e32 v3, s98
	v_mov_b32_e32 v4, 2
	global_store_dword v3, v4, s[4:5]
	v_lshlrev_b32_e32 v3, 2, v0
	v_add_u32_e32 v3, 0x4000, v3
	s_mov_b32 s99, 0
.Llb_spin_s2:
	global_load_dword v2, v3, s[4:5] sc1
	s_waitcnt vmcnt(0)
	v_cmp_gt_u32_e32 vcc, 2, v2
	s_cbranch_vccz .Llb_acq_s2
	s_sleep 1
	s_add_i32 s99, s99, 1
	s_cmp_lt_u32 s99, 0x40000
	s_cbranch_scc1 .Llb_spin_s2

.Llb_loc_s3:
	v_cmp_gt_u32_e32 vcc, 32, v0
	s_and_saveexec_b64 s[2:3], vcc
	s_cbranch_execz .Llb_done_s3
	v_readlane_b32 s4, v254, 14
	v_readlane_b32 s10, v254, 12
	v_readlane_b32 s11, v254, 13
	s_lshl_b32 s4, s4, 7
	s_add_u32 s4, s10, s4
	s_addc_u32 s5, s11, 0
	s_lshr_b32 s98, s24, 3
	s_lshl_b32 s98, s98, 2
	s_add_i32 s98, s98, 0x4000
	v_mov_b32_e32 v3, s98
	v_mov_b32_e32 v4, 3
	global_store_dword v3, v4, s[4:5]
	v_cmp_eq_u32_e32 vcc, 0, v0
	s_and_saveexec_b64 s[98:99], vcc
	v_mov_b32_e32 v5, 0x240c
	v_mov_b32_e32 v6, 1
	global_atomic_add v5, v6, s[10:11]
	s_or_b64 exec, exec, s[98:99]
	v_lshlrev_b32_e32 v3, 2, v0
	v_add_u32_e32 v3, 0x4000, v3
	s_mov_b32 s99, 0
.Llb_spin_s3:
	global_load_dword v2, v3, s[4:5] sc1
	s_waitcnt vmcnt(0)
	v_cmp_gt_u32_e32 vcc, 3, v2
	s_cbranch_vccz .Llb_acq_s3
	s_sleep 1
	s_add_i32 s99, s99, 1
	s_cmp_lt_u32 s99, 0x40000
	s_cbranch_scc1 .Llb_spin_s3

.Llb_loc_s4:
	v_cmp_gt_u32_e32 vcc, 32, v0
	s_and_saveexec_b64 s[2:3], vcc
	s_cbranch_execz .Llb_done_s4
	v_readlane_b32 s4, v254, 14
	v_readlane_b32 s10, v254, 12
	v_readlane_b32 s11, v254, 13
	s_lshl_b32 s4, s4, 7
	s_add_u32 s4, s10, s4
	s_addc_u32 s5, s11, 0
	s_lshr_b32 s98, s24, 3
	s_lshl_b32 s98, s98, 2
	s_add_i32 s98, s98, 0x4000
	v_mov_b32_e32 v3, s98
	v_mov_b32_e32 v4, 4
	global_store_dword v3, v4, s[4:5]
	v_lshlrev_b32_e32 v3, 2, v0
	v_add_u32_e32 v3, 0x4000, v3
	s_mov_b32 s99, 0
.Llb_spin_s4:
	global_load_dword v2, v3, s[4:5] sc1
	s_waitcnt vmcnt(0)
	v_cmp_gt_u32_e32 vcc, 4, v2
	s_cbranch_vccz .Llb_acq_s4
	s_sleep 1
	s_add_i32 s99, s99, 1
	s_cmp_lt_u32 s99, 0x40000
	s_cbranch_scc1 .Llb_spin_s4

.Llb_loc_s5:
	v_cmp_gt_u32_e32 vcc, 32, v0
	s_and_saveexec_b64 s[0:1], vcc
	s_cbranch_execz .Llb_done_s5
	v_readlane_b32 s4, v254, 14
	v_readlane_b32 s10, v254, 12
	v_readlane_b32 s11, v254, 13
	s_lshl_b32 s4, s4, 7
	s_add_u32 s4, s10, s4
	s_addc_u32 s5, s11, 0
	s_lshr_b32 s98, s24, 3
	s_lshl_b32 s98, s98, 2
	s_add_i32 s98, s98, 0x4000
	v_mov_b32_e32 v3, s98
	v_mov_b32_e32 v4, 5
	global_store_dword v3, v4, s[4:5]
	v_cmp_eq_u32_e32 vcc, 0, v0
	s_and_saveexec_b64 s[98:99], vcc
	v_mov_b32_e32 v5, 0x2408
	v_mov_b32_e32 v6, 1
	global_atomic_add v5, v6, s[10:11]
	s_or_b64 exec, exec, s[98:99]
	v_lshlrev_b32_e32 v3, 2, v0
	v_add_u32_e32 v3, 0x4000, v3
	s_mov_b32 s99, 0
.Llb_spin_s5:
	global_load_dword v2, v3, s[4:5] sc1
	s_waitcnt vmcnt(0)
	v_cmp_gt_u32_e32 vcc, 5, v2
	s_cbranch_vccz .Llb_acq_s5
	s_sleep 1
	s_add_i32 s99, s99, 1
	s_cmp_lt_u32 s99, 0x40000
	s_cbranch_scc1 .Llb_spin_s5

.Llb_loc_s7:
	v_cmp_gt_u32_e32 vcc, 32, v0
	s_and_saveexec_b64 s[2:3], vcc
	s_cbranch_execz .Llb_done_s7
	v_readlane_b32 s4, v254, 14
	v_readlane_b32 s10, v254, 12
	v_readlane_b32 s11, v254, 13
	s_lshl_b32 s4, s4, 7
	s_add_u32 s4, s10, s4
	s_addc_u32 s5, s11, 0
	s_lshr_b32 s98, s24, 3
	s_lshl_b32 s98, s98, 2
	s_add_i32 s98, s98, 0x4000
	v_mov_b32_e32 v3, s98
	v_mov_b32_e32 v4, 6
	global_store_dword v3, v4, s[4:5]
	v_lshlrev_b32_e32 v3, 2, v0
	v_add_u32_e32 v3, 0x4000, v3
	s_mov_b32 s99, 0
.Llb_spin_s7:
	global_load_dword v2, v3, s[4:5] sc1
	s_waitcnt vmcnt(0)
	v_cmp_gt_u32_e32 vcc, 6, v2
	s_cbranch_vccz .Llb_acq_s7
	s_sleep 1
	s_add_i32 s99, s99, 1
	s_cmp_lt_u32 s99, 0x40000
	s_cbranch_scc1 .Llb_spin_s7

.Llb_loc_s8:
	v_cmp_gt_u32_e32 vcc, 32, v0
	s_and_saveexec_b64 s[0:1], vcc
	s_cbranch_execz .Llb_done_s8
	v_readlane_b32 s4, v254, 14
	v_readlane_b32 s10, v254, 12
	v_readlane_b32 s11, v254, 13
	s_lshl_b32 s4, s4, 7
	s_add_u32 s4, s10, s4
	s_addc_u32 s5, s11, 0
	s_lshr_b32 s98, s24, 3
	s_lshl_b32 s98, s98, 2
	s_add_i32 s98, s98, 0x4000
	v_mov_b32_e32 v3, s98
	v_mov_b32_e32 v4, 7
	global_store_dword v3, v4, s[4:5]
	v_lshlrev_b32_e32 v3, 2, v0
	v_add_u32_e32 v3, 0x4000, v3
	s_mov_b32 s99, 0
.Llb_spin_s8:
	global_load_dword v2, v3, s[4:5] sc1
	s_waitcnt vmcnt(0)
	v_cmp_gt_u32_e32 vcc, 7, v2
	s_cbranch_vccz .Llb_acq_s8
	s_sleep 1
	s_add_i32 s99, s99, 1
	s_cmp_lt_u32 s99, 0x40000
	s_cbranch_scc1 .Llb_spin_s8
